# v132 + differential-attention loop: V-fragment ds_read_b128 spread one per PV MFMA gap (was bursts of four), in-group waits lgkmcnt(3)
# baseline (speedup 1.0000x reference)
.LBB0_567:
	s_waitcnt lgkmcnt(3)
	v_mfma_f32_32x32x16_bf16 v[32:47], v[124:127], v[172:175], v[32:47]
	ds_read_b128 v[188:191], v247 offset:9216
	v_exp_f32_e32 v200, v96
	v_exp_f32_e32 v201, v97
	v_exp_f32_e32 v202, v98
	v_exp_f32_e32 v203, v99
	v_cvt_pk_bf16_f32 v192, v200, v201
	v_cvt_pk_bf16_f32 v193, v202, v203
	s_waitcnt lgkmcnt(3)
	v_mfma_f32_32x32x16_bf16 v[32:47], v[120:123], v[168:171], v[32:47]
	ds_read_b128 v[184:187], v247 offset:9248
	v_exp_f32_e32 v124, v100
	v_exp_f32_e32 v125, v101
	v_exp_f32_e32 v126, v102
	v_exp_f32_e32 v127, v103
	v_cvt_pk_bf16_f32 v194, v124, v125
	v_cvt_pk_bf16_f32 v195, v126, v127
	s_waitcnt lgkmcnt(3)
	v_mfma_f32_32x32x16_bf16 v[32:47], v[116:119], v[164:167], v[32:47]
	ds_read_b128 v[180:183], v247 offset:9280
	v_exp_f32_e32 v120, v104
	v_exp_f32_e32 v121, v105
	v_exp_f32_e32 v122, v106
	v_exp_f32_e32 v123, v107
	v_cvt_pk_bf16_f32 v196, v120, v121
	v_cvt_pk_bf16_f32 v197, v122, v123
	s_waitcnt lgkmcnt(3)
	v_mfma_f32_32x32x16_bf16 v[32:47], v[112:115], v[160:163], v[32:47]
	ds_read_b128 v[176:179], v247 offset:9312
	v_exp_f32_e32 v116, v108
	v_exp_f32_e32 v117, v109
	v_exp_f32_e32 v118, v110
	v_exp_f32_e32 v119, v111
	v_cvt_pk_bf16_f32 v198, v116, v117
	v_cvt_pk_bf16_f32 v199, v118, v119
	v_add_f32_e32 v112, v202, v200
	v_add_f32_e32 v113, v203, v201
	s_waitcnt lgkmcnt(3)
	v_mfma_f32_32x32x16_bf16 v[16:31], v[188:191], v[172:175], v[16:31]
	v_add_f32_e32 v112, v124, v112
	v_add_f32_e32 v113, v125, v113
	ds_read_b128 v[96:99], v247 offset:13824
	v_add_f32_e32 v112, v126, v112
	v_add_f32_e32 v113, v127, v113
	v_exp_f32_e32 v80, v80
	v_exp_f32_e32 v81, v81
	v_add_f32_e32 v112, v120, v112
	v_add_f32_e32 v113, v121, v113
	v_cvt_pk_bf16_f32 v200, v80, v81
	v_add_f32_e32 v112, v122, v112
	v_add_f32_e32 v113, v123, v113
	v_add_f32_e32 v112, v116, v112
	v_add_f32_e32 v113, v117, v113
	v_add_f32_e32 v112, v118, v112
	v_add_f32_e32 v113, v119, v113
	v_add_f32_e32 v112, v80, v112
	v_add_f32_e32 v113, v81, v113
	s_waitcnt lgkmcnt(3)
	v_mfma_f32_32x32x16_bf16 v[16:31], v[184:187], v[168:171], v[16:31]
	ds_read_b128 v[100:103], v247 offset:13856
	v_exp_f32_e32 v80, v82
	v_exp_f32_e32 v81, v83
	v_add_f32_e32 v82, v80, v112
	v_cvt_pk_bf16_f32 v201, v80, v81
	v_add_f32_e32 v83, v81, v113
	s_waitcnt lgkmcnt(3)
	v_mfma_f32_32x32x16_bf16 v[16:31], v[180:183], v[164:167], v[16:31]
	ds_read_b128 v[104:107], v247 offset:13888
	v_exp_f32_e32 v80, v84
	v_exp_f32_e32 v81, v85
	v_add_f32_e32 v82, v80, v82
	v_cvt_pk_bf16_f32 v202, v80, v81
	v_add_f32_e32 v83, v81, v83
	s_waitcnt lgkmcnt(3)
	v_mfma_f32_32x32x16_bf16 v[16:31], v[176:179], v[160:163], v[16:31]
	ds_read_b128 v[108:111], v247 offset:13920
	v_exp_f32_e32 v80, v86
	v_exp_f32_e32 v81, v87
	v_add_f32_e32 v82, v80, v82
	v_cvt_pk_bf16_f32 v203, v80, v81
	v_add_f32_e32 v83, v81, v83
	s_waitcnt lgkmcnt(3)
	v_mfma_f32_32x32x16_bf16 v[0:15], v[96:99], v[172:175], v[0:15]
	v_exp_f32_e32 v80, v88
	v_exp_f32_e32 v81, v89
	v_add_f32_e32 v82, v80, v82
	v_cvt_pk_bf16_f32 v204, v80, v81
	v_add_f32_e32 v83, v81, v83
	s_waitcnt lgkmcnt(2)
	v_mfma_f32_32x32x16_bf16 v[0:15], v[100:103], v[168:171], v[0:15]
	v_exp_f32_e32 v80, v90
	v_exp_f32_e32 v81, v91
	v_add_f32_e32 v82, v80, v82
	v_cvt_pk_bf16_f32 v205, v80, v81
	v_add_f32_e32 v83, v81, v83
	s_waitcnt lgkmcnt(1)
	v_mfma_f32_32x32x16_bf16 v[0:15], v[104:107], v[164:167], v[0:15]
	v_exp_f32_e32 v80, v92
	v_exp_f32_e32 v81, v93
	v_add_f32_e32 v82, v80, v82
	v_cvt_pk_bf16_f32 v206, v80, v81
	v_add_f32_e32 v83, v81, v83
	s_waitcnt lgkmcnt(0)
	v_mfma_f32_32x32x16_bf16 v[0:15], v[108:111], v[160:163], v[0:15]
	v_exp_f32_e32 v80, v94
	v_exp_f32_e32 v81, v95
	v_add_f32_e32 v82, v80, v82
	v_cvt_pk_bf16_f32 v207, v80, v81
	v_add_f32_e32 v83, v81, v83
	v_add_f32_e32 v252, v82, v83
	v_fmac_f32_e32 v252, v223, v224
	v_mov_b32_e32 v163, v207
	v_mov_b32_e32 v162, v206
	v_mov_b32_e32 v161, v205
	v_mov_b32_e32 v160, v204
	v_mov_b32_e32 v167, v203
	v_mov_b32_e32 v166, v202
	v_mov_b32_e32 v165, v201
	v_mov_b32_e32 v164, v200
	v_mov_b32_e32 v171, v199
	v_mov_b32_e32 v170, v198
	v_mov_b32_e32 v169, v197
	v_mov_b32_e32 v168, v196
	v_mov_b32_e32 v175, v195
	v_mov_b32_e32 v174, v194
	v_mov_b32_e32 v173, v193
	v_mov_b32_e32 v172, v192
	s_branch .LBB0_570
